# on top of v16: the single cooperative-groups grid sync after phase 0 is replaced by the kernel's own XCD-hierarchical grid barrier (same release/acquire semantics as every other phase boundary)
# speedup vs baseline: 1.0107x; 1.0050x over previous
; #define LAS __attribute__((address_space(3)))
; __global__ void __launch_bounds__(512, 2) fwd(Args a) {
;     extern __shared__ __attribute__((aligned(16))) unsigned char lds[];
;     cg::grid_group grid = cg::this_grid();
;     LAS unsigned long long* ptab = (LAS unsigned long long*)((LAS unsigned char*)lds + PTAB_OFF);
;     if (threadIdx.x == 0) {
; #pragma unroll
;         for (int i = 0; i < 13; ++i) ptab[i] = (unsigned long long)a.in[i];
;         ptab[13] = (unsigned long long)a.out; ptab[14] = (unsigned long long)a.ws; ptab[15] = (unsigned long long)a.ngroups; ptab[16] = 0ull;
;         ((LAS unsigned*)(ptab + 24))[0] = 0u; ((LAS unsigned*)(ptab + 24))[1] = 0u; }
_Z3fwd4Args:
	s_mov_b32 s100, 0
	s_load_dwordx2 s[50:51], s[0:1], 0x80
	s_load_dword s3, s[0:1], 0x88
	s_add_u32 s4, s0, 0x80
	s_addc_u32 s5, s1, 0
	v_and_b32_e32 v186, 0x3ff, v0
	v_writelane_b32 v236, s4, 0
	s_mov_b32 s22, 0
	v_cmp_eq_u32_e64 s[76:77], 0, v186
	v_writelane_b32 v236, s5, 1
	s_and_saveexec_b64 s[20:21], s[76:77]
	s_cbranch_execz .LBB0_2
	s_load_dwordx16 s[4:19], s[0:1], 0x0
	s_add_i32 s23, 0, 0x26000
	v_mov_b32_e32 v1, s23
	s_mov_b32 s23, s22
	s_waitcnt lgkmcnt(0)
	v_mov_b32_e32 v2, s4
	v_mov_b32_e32 v3, s5
	v_mov_b32_e32 v4, s6
	v_mov_b32_e32 v5, s7
	s_add_i32 s4, 0, 0x26010
	ds_write_b128 v1, v[2:5]
	v_mov_b32_e32 v2, s8
	v_mov_b32_e32 v3, s9
	v_mov_b32_e32 v4, s10
	v_mov_b32_e32 v5, s11
	v_mov_b32_e32 v1, s4
	s_add_i32 s4, 0, 0x26020
	ds_write_b128 v1, v[2:5]
	v_mov_b32_e32 v2, s12
	v_mov_b32_e32 v3, s13
	v_mov_b32_e32 v4, s14
	v_mov_b32_e32 v5, s15
	v_mov_b32_e32 v1, s4
	s_add_i32 s12, 0, 0x26030
	s_load_dwordx8 s[4:11], s[0:1], 0x40
	ds_write_b128 v1, v[2:5]
	v_mov_b32_e32 v2, s16
	v_mov_b32_e32 v3, s17
	v_mov_b32_e32 v4, s18
	v_mov_b32_e32 v5, s19
	v_mov_b32_e32 v1, s12
	ds_write_b128 v1, v[2:5]
	s_load_dwordx2 s[16:17], s[0:1], 0x70
	s_load_dwordx4 s[12:15], s[0:1], 0x60
	s_waitcnt lgkmcnt(0)
	v_mov_b32_e32 v2, s4
	s_add_i32 s4, 0, 0x26040
	s_load_dword s0, s[0:1], 0x78
	v_mov_b32_e32 v3, s5
	v_mov_b32_e32 v4, s6
	v_mov_b32_e32 v5, s7
	v_mov_b32_e32 v1, s4
	s_add_i32 s4, 0, 0x26050
	ds_write_b128 v1, v[2:5]
	v_mov_b32_e32 v2, s8
	v_mov_b32_e32 v3, s9
	v_mov_b32_e32 v4, s10
	v_mov_b32_e32 v5, s11
	v_mov_b32_e32 v1, s4
	ds_write_b128 v1, v[2:5]
	s_add_i32 s1, 0, 0x26060
	v_mov_b64_e32 v[2:3], s[12:13]
	v_mov_b32_e32 v1, s1
	v_mov_b64_e32 v[4:5], s[14:15]
	ds_write_b128 v1, v[2:5]
	s_waitcnt lgkmcnt(0)
	s_ashr_i32 s1, s0, 31
	v_mov_b32_e32 v4, s0
	s_add_i32 s0, 0, 0x26070
	v_mov_b32_e32 v2, s16
	v_mov_b32_e32 v3, s17
	v_mov_b32_e32 v5, s1
	v_mov_b32_e32 v1, s0
	s_add_i32 s0, 0, 0x26080
	ds_write_b128 v1, v[2:5]
	v_mov_b32_e32 v1, s0
	v_mov_b64_e32 v[2:3], s[22:23]
	s_add_i32 s0, 0, 0x260c0
	ds_write_b64 v1, v[2:3]
	v_mov_b32_e32 v1, s0
	ds_write_b64 v1, v[2:3]

; __global__ void __launch_bounds__(512, 2) fwd(Args a) {
;     ...
;         if ((int)ldptr(ptab, 16) == 0) grid.sync();
.LBB0_41:
	v_mov_b32_e32 v0, s78
	s_waitcnt lgkmcnt(0)
	ds_read_b64 v[0:1], v0
	s_waitcnt lgkmcnt(0)
	v_readfirstlane_b32 s0, v0
	s_cmp_lg_u32 s0, 0
	s_cbranch_scc1 .LBB0_53
	s_mov_b32 s100, 1
	s_branch .LBB0_208

; #define GSYNC() do { XcdBarrier b_; b_.bar = (unsigned*)(ldptr(ptab, 14) + WS_BAR); b_.x = xb_xcc_id(); b_.st = (volatile LAS unsigned*)(ptab + 24); xcd_barrier(b_); } while (0)
; __device__ __forceinline__ void xcd_barrier(const XcdBarrier& b) {
;     ...
;     __syncthreads();
; }
; __global__ void __launch_bounds__(512, 2) fwd(Args a) {
;     ...
;         GSYNC();
;         {
;             const Ctx c = load_ctx(ptab);
;             if (__builtin_amdgcn_readfirstlane(c.tid) >= 256) __builtin_amdgcn_s_setprio(1);
.LBB0_252:
	s_or_b64 exec, exec, s[34:35]
	s_waitcnt lgkmcnt(0)
	s_barrier
	s_cmp_eq_u32 s100, 1
	s_cbranch_scc0 .Lmy_gs1_cont
	s_mov_b32 s100, 0
	s_branch .LBB0_53
.Lmy_gs1_cont:
	v_mov_b32_e32 v0, s78
	ds_read_b64 v[0:1], v0
	v_mov_b32_e32 v178, v186
	s_waitcnt lgkmcnt(0)
	v_readfirstlane_b32 s0, v0
	v_mov_b32_e32 v0, s79
	ds_read_b64 v[0:1], v0
	s_waitcnt lgkmcnt(0)
	v_readfirstlane_b32 s1, v0
	v_mov_b32_e32 v0, s80
	ds_read_b64 v[0:1], v0
	v_readfirstlane_b32 s6, v178
	s_cmpk_lt_i32 s6, 0x100
	s_waitcnt lgkmcnt(0)
	v_readfirstlane_b32 s5, v1
	v_readfirstlane_b32 s4, v0
	s_cbranch_scc1 .LBB0_254
	s_setprio 1

; __global__ void __launch_bounds__(512, 2) fwd(Args a) {
	.amdhsa_kernel _Z3fwd4Args
		.amdhsa_group_segment_fixed_size 0
		.amdhsa_private_segment_fixed_size 0
		.amdhsa_kernarg_size 384
		.amdhsa_user_sgpr_count 2
		.amdhsa_user_sgpr_dispatch_ptr 0
		.amdhsa_user_sgpr_queue_ptr 0
		.amdhsa_user_sgpr_kernarg_segment_ptr 1
		.amdhsa_user_sgpr_dispatch_id 0
		.amdhsa_user_sgpr_kernarg_preload_length 0
		.amdhsa_user_sgpr_kernarg_preload_offset 0
		.amdhsa_user_sgpr_private_segment_size 0
		.amdhsa_uses_dynamic_stack 0
		.amdhsa_enable_private_segment 0
		.amdhsa_system_sgpr_workgroup_id_x 1
		.amdhsa_system_sgpr_workgroup_id_y 0
		.amdhsa_system_sgpr_workgroup_id_z 0
		.amdhsa_system_sgpr_workgroup_info 0
		.amdhsa_system_vgpr_workitem_id 2
		.amdhsa_next_free_vgpr 237
		.amdhsa_next_free_sgpr 102
		.amdhsa_accum_offset 240
		.amdhsa_reserve_vcc 1
		.amdhsa_float_round_mode_32 0
		.amdhsa_float_round_mode_16_64 0
		.amdhsa_float_denorm_mode_32 3
		.amdhsa_float_denorm_mode_16_64 3
		.amdhsa_dx10_clamp 1
		.amdhsa_ieee_mode 1
		.amdhsa_fp16_overflow 0
		.amdhsa_tg_split 0
		.amdhsa_exception_fp_ieee_invalid_op 0
		.amdhsa_exception_fp_denorm_src 0
		.amdhsa_exception_fp_ieee_div_zero 0
		.amdhsa_exception_fp_ieee_overflow 0
		.amdhsa_exception_fp_ieee_underflow 0
		.amdhsa_exception_fp_ieee_inexact 0
		.amdhsa_exception_int_div_zero 0
	.end_amdhsa_kernel

; __global__ void __launch_bounds__(512, 2) fwd(Args a) {
amdhsa.kernels:
  - .agpr_count:     0
    .args:
      - .offset:         0
        .size:           128
        .value_kind:     by_value
      - .offset:         128
        .size:           4
        .value_kind:     hidden_block_count_x
      - .offset:         132
        .size:           4
        .value_kind:     hidden_block_count_y
      - .offset:         136
        .size:           4
        .value_kind:     hidden_block_count_z
      - .offset:         140
        .size:           2
        .value_kind:     hidden_group_size_x
      - .offset:         142
        .size:           2
        .value_kind:     hidden_group_size_y
      - .offset:         144
        .size:           2
        .value_kind:     hidden_group_size_z
      - .offset:         146
        .size:           2
        .value_kind:     hidden_remainder_x
      - .offset:         148
        .size:           2
        .value_kind:     hidden_remainder_y
      - .offset:         150
        .size:           2
        .value_kind:     hidden_remainder_z
      - .offset:         168
        .size:           8
        .value_kind:     hidden_global_offset_x
      - .offset:         176
        .size:           8
        .value_kind:     hidden_global_offset_y
      - .offset:         184
        .size:           8
        .value_kind:     hidden_global_offset_z
      - .offset:         192
        .size:           2
        .value_kind:     hidden_grid_dims
      - .offset:         216
        .size:           8
        .value_kind:     hidden_multigrid_sync_arg
      - .offset:         248
        .size:           4
        .value_kind:     hidden_dynamic_lds_size
    .group_segment_fixed_size: 0
    .kernarg_segment_align: 8
    .kernarg_segment_size: 384
    .language:       OpenCL C
    .language_version:
      - 2
      - 0
    .max_flat_workgroup_size: 512
    .name:           _Z3fwd4Args
    .private_segment_fixed_size: 0
    .sgpr_count:     108
    .sgpr_spill_count: 64
    .symbol:         _Z3fwd4Args.kd
    .uniform_work_group_size: 1
    .uses_dynamic_stack: false
    .vgpr_count:     237
    .vgpr_spill_count: 0
    .wavefront_size: 64
